# speedup vs baseline: 1.0247x; 1.0110x over previous
; #define PG8_WAIT_V(n) asm volatile("s_waitcnt vmcnt(" #n ")" ::: "memory")
; #define PG8_BAR __builtin_amdgcn_s_barrier()
; template <class Epi, class Sched>
; __device__ __forceinline__ void gemm_phase(LAS unsigned char* lds, const Gemm g, const Sched& S, const Epi& E) {
;     int tid_ = threadIdx.x; asm volatile("" : "+v"(tid_));
;     const int tid = tid_, wid = __builtin_amdgcn_readfirstlane(tid >> 6), lane = tid & 63, wr = wid >> 2, wc = wid & 3, fr = lane & 15, fq = lane >> 4;
;     ...
;     if (wr == 1) PG8_BAR;
;     PG8_WAIT_V(4); PG8_BAR;
.LBB0_14:
	s_nop 0
	v_readfirstlane_b32 s100, v204
	s_nop 3
	s_lshr_b32 s100, s100, 6
	s_cmp_lt_u32 s100, 4
	s_cbranch_scc0 .Lmy_prio_done
	s_setprio 1
